# side_gemm1: operand rows fetched with fully coalesced loads (8 rows x 128 B per instruction) and re-laid out for the MFMA through a private swizzled LDS area, instead of strided 64-byte pieces
# speedup vs baseline: 1.0032x; 1.0032x over previous
; #define GAS __attribute__((address_space(1)))
; __device__ __forceinline__ f32x4 mfma16(const bf16x8& a, const bf16x8& b, const f32x4& c) { return __builtin_amdgcn_mfma_f32_16x16x32_bf16(a, b, c, 0, 0, 0); }
; template <class F> __device__ __forceinline__ void skinny_tile(const GAS bf16* A, int lda, const GAS bf16* Bt, int K, int n0, int lane, F&& epi) {
;     const int fr = lane & 15, fq = lane >> 4;
;     const GAS bf16* ap = A + (size_t)fr * lda + fq * 8; const GAS bf16* bp = Bt + (size_t)(n0 + fr) * K + fq * 8;
;     f32x4 acc0 = {0.f, 0.f, 0.f, 0.f}, acc1 = {0.f, 0.f, 0.f, 0.f};
;     bf16x8 a[4], bb[4], a2[4], b2[4];
; #pragma unroll
;     for (int i = 0; i < 4; ++i) { a[i] = *(const GAS bf16x8*)(ap + i * 32); bb[i] = *(const GAS bf16x8*)(bp + i * 32); }
;     for (int k = 0; k < K; k += 256) {
; #pragma unroll
;         for (int i = 0; i < 4; ++i) { a2[i] = *(const GAS bf16x8*)(ap + k + 128 + i * 32); b2[i] = *(const GAS bf16x8*)(bp + k + 128 + i * 32); }
; #pragma unroll
;         for (int i = 0; i < 4; i += 2) { acc0 = mfma16(a[i], bb[i], acc0); acc1 = mfma16(a[i + 1], bb[i + 1], acc1); }
;         if (k + 256 < K) {
; #pragma unroll
;             for (int i = 0; i < 4; ++i) { a[i] = *(const GAS bf16x8*)(ap + k + 256 + i * 32); bb[i] = *(const GAS bf16x8*)(bp + k + 256 + i * 32); } }
; #pragma unroll
;         for (int i = 0; i < 4; i += 2) { acc0 = mfma16(a2[i], b2[i], acc0); acc1 = mfma16(a2[i + 1], b2[i + 1], acc1); } }
; __device__ __forceinline__ void side_gemm1(const Params& P, int seg) {
;     ...
;     for (int it = gw; it < nrt * 4; it += NGW) { const int rt = it >> 2, r0 = (rt < RS / 16) ? rt * 16 : RS + 48;
;         skinny_tile(xb + (size_t)r0 * DM, DM, Wt + (size_t)NPROJ * DM, DM, (it & 3) * 16, lane, [&](int row, int j, int col, float v) {
.Lsg1_new:
	s_mov_b32 s100, 0
	v_or_b32_e32 v16, v16, v29
	v_lshlrev_b32_e32 v174, 2, v17
	v_ashrrev_i32_e32 v17, 31, v16
	v_lshl_add_u64 v[18:19], v[16:17], 2, s[14:15]
	v_mov_b64_e32 v[248:249], v[18:19]
	global_load_dword v243, v[248:249], off
	global_load_dword v244, v174, s[44:45]
	global_load_dword v245, v[248:249], off offset:4
	global_load_dword v246, v[248:249], off offset:8
	global_load_dword v247, v[248:249], off offset:12
	v_lshrrev_b32_e32 v116, 6, v172
	v_and_b32_e32 v117, 3, v116
	v_and_b32_e32 v18, 63, v172
	v_lshrrev_b32_e32 v19, 3, v18
	v_and_b32_e32 v32, 7, v18
	v_lshlrev_b32_e32 v236, 12, v19
	v_lshl_add_u32 v236, v32, 4, v236
	v_lshl_add_u32 v236, v116, 9, v236
	v_add_u32_e32 v237, 0x8000, v236
	v_and_b32_e32 v118, 15, v18
	v_lshlrev_b32_e32 v118, 12, v118
	v_and_b32_e32 v32, 48, v18
	v_add_u32_e32 v118, v118, v32
	v_sub_u32_e32 v32, v236, v118
	v_ashrrev_i32_e32 v33, 31, v32
	v_lshl_add_u64 v[232:233], v[4:5], 0, v[32:33]
	s_mov_b64 s[54:55], 0x8000
	v_lshl_add_u64 v[234:235], v[232:233], 0, s[54:55]
	v_cmp_gt_u32_e64 s[54:55], 4, v116
	v_mov_b32_e32 v34, 0x10000
	v_mov_b32_e32 v32, 0xffff0000
	s_nop 1
	v_cndmask_b32_e64 v32, v32, v34, s[54:55]
	v_ashrrev_i32_e32 v33, 31, v32
	v_lshl_add_u64 v[20:21], v[232:233], 0, v[32:33]
	v_lshl_add_u64 v[250:251], v[234:235], 0, v[32:33]
	s_add_u32 s46, s40, 0x5000000
	s_addc_u32 s47, s41, 0
	s_add_u32 s48, s46, 0x10000
	s_addc_u32 s49, s47, 0
	s_add_u32 s50, s46, 0x20000
	s_addc_u32 s51, s47, 0
	s_add_u32 s52, s46, 0x30000
	s_addc_u32 s53, s47, 0
	v_mul_u32_u24_e32 v22, 0x3000, v116
	v_lshl_add_u32 v22, v19, 7, v22
	v_lshrrev_b32_e32 v118, 4, v18
	v_and_b32_e32 v18, 7, v18
	v_xor_b32_e32 v19, v18, v118
	v_lshl_add_u32 v118, v19, 4, v22
	v_xor_b32_e32 v118, 64, v118
	v_lshl_add_u32 v22, v19, 4, v22
	v_and_b32_e32 v18, 15, v172
	v_bfe_u32 v19, v172, 4, 2
	v_lshrrev_b32_e32 v68, 1, v18
	v_xor_b32_e32 v19, v19, v68
	v_lshlrev_b32_e32 v19, 4, v19
	v_lshl_add_u32 v19, v18, 7, v19
	v_mul_u32_u24_e32 v18, 0x3000, v116
	v_add_u32_e32 v18, v18, v19
	v_xor_b32_e32 v19, 64, v18
	global_load_dwordx4 v[68:71], v[232:233], off
	global_load_dwordx4 v[72:75], v[234:235], off
	global_load_dwordx4 v[76:79], v[20:21], off
	global_load_dwordx4 v[80:83], v[250:251], off
	global_load_dwordx4 v[84:87], v236, s[46:47]
	global_load_dwordx4 v[88:91], v237, s[46:47]
	global_load_dwordx4 v[92:95], v236, s[48:49]
	global_load_dwordx4 v[96:99], v237, s[48:49]
	global_load_dwordx4 v[100:103], v236, s[50:51]
	global_load_dwordx4 v[104:107], v237, s[50:51]
	global_load_dwordx4 v[108:111], v236, s[52:53]
	global_load_dwordx4 v[112:115], v237, s[52:53]
	global_load_dwordx4 v[120:123], v[232:233], off offset:128
	global_load_dwordx4 v[124:127], v[234:235], off offset:128
	global_load_dwordx4 v[128:131], v[20:21], off offset:128
	global_load_dwordx4 v[132:135], v[250:251], off offset:128
	global_load_dwordx4 v[136:139], v236, s[46:47] offset:128
	global_load_dwordx4 v[140:143], v237, s[46:47] offset:128
	global_load_dwordx4 v[144:147], v236, s[48:49] offset:128
	global_load_dwordx4 v[148:151], v237, s[48:49] offset:128
	global_load_dwordx4 v[152:155], v236, s[50:51] offset:128
	global_load_dwordx4 v[156:159], v237, s[50:51] offset:128
	global_load_dwordx4 v[160:163], v236, s[52:53] offset:128
	global_load_dwordx4 v[164:167], v237, s[52:53] offset:128
	global_load_dwordx4 v[184:187], v[232:233], off offset:256
	global_load_dwordx4 v[188:191], v[234:235], off offset:256
	global_load_dwordx4 v[192:195], v[20:21], off offset:256
	global_load_dwordx4 v[196:199], v[250:251], off offset:256
	global_load_dwordx4 v[200:203], v236, s[46:47] offset:256
	global_load_dwordx4 v[204:207], v237, s[46:47] offset:256
	global_load_dwordx4 v[208:211], v236, s[48:49] offset:256
	global_load_dwordx4 v[212:215], v237, s[48:49] offset:256
	global_load_dwordx4 v[216:219], v236, s[50:51] offset:256
	global_load_dwordx4 v[220:223], v237, s[50:51] offset:256
	global_load_dwordx4 v[224:227], v236, s[52:53] offset:256
	global_load_dwordx4 v[228:231], v237, s[52:53] offset:256
	s_waitcnt vmcnt(24)
	ds_write_b128 v22, v[68:71]
	ds_write_b128 v118, v[72:75] offset:1024
	ds_write_b128 v22, v[76:79] offset:2048
	ds_write_b128 v118, v[80:83] offset:3072
	ds_write_b128 v22, v[84:87] offset:4096
	ds_write_b128 v118, v[88:91] offset:5120
	ds_write_b128 v22, v[92:95] offset:6144
	ds_write_b128 v118, v[96:99] offset:7168
	ds_write_b128 v22, v[100:103] offset:8192
	ds_write_b128 v118, v[104:107] offset:9216
	ds_write_b128 v22, v[108:111] offset:10240
	ds_write_b128 v118, v[112:115] offset:11264
	ds_read_b128 v[68:71], v18
	ds_read_b128 v[72:75], v19
	ds_read_b128 v[76:79], v18 offset:2048
	ds_read_b128 v[80:83], v19 offset:2048
	ds_read_b128 v[84:87], v18 offset:4096
	ds_read_b128 v[88:91], v19 offset:4096
	ds_read_b128 v[92:95], v18 offset:6144
	ds_read_b128 v[96:99], v19 offset:6144
	ds_read_b128 v[100:103], v18 offset:8192
	ds_read_b128 v[104:107], v19 offset:8192
	ds_read_b128 v[108:111], v18 offset:10240
	ds_read_b128 v[112:115], v19 offset:10240
	s_waitcnt lgkmcnt(0)
; #define GAS __attribute__((address_space(1)))
; __device__ __forceinline__ f32x4 mfma16(const bf16x8& a, const bf16x8& b, const f32x4& c) { return __builtin_amdgcn_mfma_f32_16x16x32_bf16(a, b, c, 0, 0, 0); }
; template <class F> __device__ __forceinline__ void skinny_tile(const GAS bf16* A, int lda, const GAS bf16* Bt, int K, int n0, int lane, F&& epi) {
;     const int fr = lane & 15, fq = lane >> 4;
;     const GAS bf16* ap = A + (size_t)fr * lda + fq * 8; const GAS bf16* bp = Bt + (size_t)(n0 + fr) * K + fq * 8;
;     f32x4 acc0 = {0.f, 0.f, 0.f, 0.f}, acc1 = {0.f, 0.f, 0.f, 0.f};
;     bf16x8 a[4], bb[4], a2[4], b2[4];
; #pragma unroll
;     for (int i = 0; i < 4; ++i) { a[i] = *(const GAS bf16x8*)(ap + i * 32); bb[i] = *(const GAS bf16x8*)(bp + i * 32); }
;     for (int k = 0; k < K; k += 256) {
; #pragma unroll
;         for (int i = 0; i < 4; ++i) { a2[i] = *(const GAS bf16x8*)(ap + k + 128 + i * 32); b2[i] = *(const GAS bf16x8*)(bp + k + 128 + i * 32); }
; #pragma unroll
;         for (int i = 0; i < 4; i += 2) { acc0 = mfma16(a[i], bb[i], acc0); acc1 = mfma16(a[i + 1], bb[i + 1], acc1); }
;         if (k + 256 < K) {
; #pragma unroll
;             for (int i = 0; i < 4; ++i) { a[i] = *(const GAS bf16x8*)(ap + k + 256 + i * 32); bb[i] = *(const GAS bf16x8*)(bp + k + 256 + i * 32); } }
; #pragma unroll
;         for (int i = 0; i < 4; i += 2) { acc0 = mfma16(a2[i], b2[i], acc0); acc1 = mfma16(a2[i + 1], b2[i + 1], acc1); } }
	v_mfma_f32_16x16x32_bf16 v[36:39], v[68:71], v[84:87], 0
	v_mfma_f32_16x16x32_bf16 v[40:43], v[68:71], v[92:95], 0
	v_mfma_f32_16x16x32_bf16 v[44:47], v[68:71], v[100:103], 0
	v_mfma_f32_16x16x32_bf16 v[48:51], v[68:71], v[108:111], 0
	v_mfma_f32_16x16x32_bf16 v[52:55], v[76:79], v[84:87], 0
	v_mfma_f32_16x16x32_bf16 v[56:59], v[76:79], v[92:95], 0
	v_mfma_f32_16x16x32_bf16 v[60:63], v[76:79], v[100:103], 0
	v_mfma_f32_16x16x32_bf16 v[64:67], v[76:79], v[108:111], 0
	v_mfma_f32_16x16x32_bf16 v[36:39], v[72:75], v[88:91], v[36:39]
	v_mfma_f32_16x16x32_bf16 v[40:43], v[72:75], v[96:99], v[40:43]
	v_mfma_f32_16x16x32_bf16 v[44:47], v[72:75], v[104:107], v[44:47]
	v_mfma_f32_16x16x32_bf16 v[48:51], v[72:75], v[112:115], v[48:51]
	v_mfma_f32_16x16x32_bf16 v[52:55], v[80:83], v[88:91], v[52:55]
	v_mfma_f32_16x16x32_bf16 v[56:59], v[80:83], v[96:99], v[56:59]
	v_mfma_f32_16x16x32_bf16 v[60:63], v[80:83], v[104:107], v[60:63]
	v_mfma_f32_16x16x32_bf16 v[64:67], v[80:83], v[112:115], v[64:67]
	global_load_dwordx4 v[68:71], v[232:233], off offset:384
	global_load_dwordx4 v[72:75], v[234:235], off offset:384
	global_load_dwordx4 v[76:79], v[20:21], off offset:384
	global_load_dwordx4 v[80:83], v[250:251], off offset:384
	global_load_dwordx4 v[84:87], v236, s[46:47] offset:384
	global_load_dwordx4 v[88:91], v237, s[46:47] offset:384
	global_load_dwordx4 v[92:95], v236, s[48:49] offset:384
	global_load_dwordx4 v[96:99], v237, s[48:49] offset:384
	global_load_dwordx4 v[100:103], v236, s[50:51] offset:384
	global_load_dwordx4 v[104:107], v237, s[50:51] offset:384
	global_load_dwordx4 v[108:111], v236, s[52:53] offset:384
	global_load_dwordx4 v[112:115], v237, s[52:53] offset:384
	s_waitcnt vmcnt(24)
	ds_write_b128 v22, v[120:123]
	ds_write_b128 v118, v[124:127] offset:1024
	ds_write_b128 v22, v[128:131] offset:2048
	ds_write_b128 v118, v[132:135] offset:3072
	ds_write_b128 v22, v[136:139] offset:4096
	ds_write_b128 v118, v[140:143] offset:5120
	ds_write_b128 v22, v[144:147] offset:6144
	ds_write_b128 v118, v[148:151] offset:7168
	ds_write_b128 v22, v[152:155] offset:8192
	ds_write_b128 v118, v[156:159] offset:9216
	ds_write_b128 v22, v[160:163] offset:10240
	ds_write_b128 v118, v[164:167] offset:11264
	ds_read_b128 v[120:123], v18
	ds_read_b128 v[124:127], v19
	ds_read_b128 v[128:131], v18 offset:2048
	ds_read_b128 v[132:135], v19 offset:2048
	ds_read_b128 v[136:139], v18 offset:4096
	ds_read_b128 v[140:143], v19 offset:4096
	ds_read_b128 v[144:147], v18 offset:6144
	ds_read_b128 v[148:151], v19 offset:6144
	ds_read_b128 v[152:155], v18 offset:8192
	ds_read_b128 v[156:159], v19 offset:8192
	ds_read_b128 v[160:163], v18 offset:10240
	ds_read_b128 v[164:167], v19 offset:10240
	s_waitcnt lgkmcnt(0)
	v_mfma_f32_16x16x32_bf16 v[36:39], v[120:123], v[136:139], v[36:39]
	v_mfma_f32_16x16x32_bf16 v[40:43], v[120:123], v[144:147], v[40:43]
	v_mfma_f32_16x16x32_bf16 v[44:47], v[120:123], v[152:155], v[44:47]
	v_mfma_f32_16x16x32_bf16 v[48:51], v[120:123], v[160:163], v[48:51]
	v_mfma_f32_16x16x32_bf16 v[52:55], v[128:131], v[136:139], v[52:55]
	v_mfma_f32_16x16x32_bf16 v[56:59], v[128:131], v[144:147], v[56:59]
	v_mfma_f32_16x16x32_bf16 v[60:63], v[128:131], v[152:155], v[60:63]
	v_mfma_f32_16x16x32_bf16 v[64:67], v[128:131], v[160:163], v[64:67]
	v_mfma_f32_16x16x32_bf16 v[36:39], v[124:127], v[140:143], v[36:39]
	v_mfma_f32_16x16x32_bf16 v[40:43], v[124:127], v[148:151], v[40:43]
	v_mfma_f32_16x16x32_bf16 v[44:47], v[124:127], v[156:159], v[44:47]
	v_mfma_f32_16x16x32_bf16 v[48:51], v[124:127], v[164:167], v[48:51]
	v_mfma_f32_16x16x32_bf16 v[52:55], v[132:135], v[140:143], v[52:55]
	v_mfma_f32_16x16x32_bf16 v[56:59], v[132:135], v[148:151], v[56:59]
	v_mfma_f32_16x16x32_bf16 v[60:63], v[132:135], v[156:159], v[60:63]
	v_mfma_f32_16x16x32_bf16 v[64:67], v[132:135], v[164:167], v[64:67]
	s_waitcnt vmcnt(12)
	ds_write_b128 v22, v[184:187]
	ds_write_b128 v118, v[188:191] offset:1024
	ds_write_b128 v22, v[192:195] offset:2048
	ds_write_b128 v118, v[196:199] offset:3072
	ds_write_b128 v22, v[200:203] offset:4096
	ds_write_b128 v118, v[204:207] offset:5120
	ds_write_b128 v22, v[208:211] offset:6144
	ds_write_b128 v118, v[212:215] offset:7168
	ds_write_b128 v22, v[216:219] offset:8192
	ds_write_b128 v118, v[220:223] offset:9216
	ds_write_b128 v22, v[224:227] offset:10240
	ds_write_b128 v118, v[228:231] offset:11264
	ds_read_b128 v[184:187], v18
	ds_read_b128 v[188:191], v19
	ds_read_b128 v[192:195], v18 offset:2048
	ds_read_b128 v[196:199], v19 offset:2048
	ds_read_b128 v[200:203], v18 offset:4096
	ds_read_b128 v[204:207], v19 offset:4096
	ds_read_b128 v[208:211], v18 offset:6144
	ds_read_b128 v[212:215], v19 offset:6144
	ds_read_b128 v[216:219], v18 offset:8192
	ds_read_b128 v[220:223], v19 offset:8192
	ds_read_b128 v[224:227], v18 offset:10240
	ds_read_b128 v[228:231], v19 offset:10240
	s_waitcnt lgkmcnt(0)
; #define GAS __attribute__((address_space(1)))
; template <class F> __device__ __forceinline__ void skinny_tile(const GAS bf16* A, int lda, const GAS bf16* Bt, int K, int n0, int lane, F&& epi) {
;     const int fr = lane & 15, fq = lane >> 4;
;     const GAS bf16* ap = A + (size_t)fr * lda + fq * 8; const GAS bf16* bp = Bt + (size_t)(n0 + fr) * K + fq * 8;
;     f32x4 acc0 = {0.f, 0.f, 0.f, 0.f}, acc1 = {0.f, 0.f, 0.f, 0.f};
;     bf16x8 a[4], bb[4], a2[4], b2[4];
; #pragma unroll
;     for (int i = 0; i < 4; ++i) { a[i] = *(const GAS bf16x8*)(ap + i * 32); bb[i] = *(const GAS bf16x8*)(bp + i * 32); }
;     for (int k = 0; k < K; k += 256) {
; #pragma unroll
;         for (int i = 0; i < 4; ++i) { a2[i] = *(const GAS bf16x8*)(ap + k + 128 + i * 32); b2[i] = *(const GAS bf16x8*)(bp + k + 128 + i * 32); }
; #pragma unroll
;         for (int i = 0; i < 4; i += 2) { acc0 = mfma16(a[i], bb[i], acc0); acc1 = mfma16(a[i + 1], bb[i + 1], acc1); }
;         if (k + 256 < K) {
; #pragma unroll
;             for (int i = 0; i < 4; ++i) { a[i] = *(const GAS bf16x8*)(ap + k + 256 + i * 32); bb[i] = *(const GAS bf16x8*)(bp + k + 256 + i * 32); } }
; #pragma unroll
;         for (int i = 0; i < 4; i += 2) { acc0 = mfma16(a2[i], b2[i], acc0); acc1 = mfma16(a2[i + 1], b2[i + 1], acc1); } }
; template <class F> __device__ __forceinline__ void skinny_tile_sk(const GAS bf16* A, int lda, const GAS bf16* Bt, int K, int n0, int wave, int lane, float* red, F&& epi) {
;     const int fr = lane & 15, fq = lane >> 4, kc = K >> 3;
;     const GAS bf16* ap = A + (size_t)fr * lda + wave * kc + fq * 8; const GAS bf16* bp = Bt + (size_t)(n0 + fr) * K + wave * kc + fq * 8;
;     f32x4 acc0 = {0.f, 0.f, 0.f, 0.f}, acc1 = {0.f, 0.f, 0.f, 0.f};
;     for (int k = 0; k < kc; k += 256) { bf16x8 a[8], bb[8];
; #pragma unroll
;         for (int i = 0; i < 8; ++i) { a[i] = *(const GAS bf16x8*)(ap + k + i * 32); bb[i] = *(const GAS bf16x8*)(bp + k + i * 32); }
; #pragma unroll
;         for (int i = 0; i < 8; i += 2) { acc0 = mfma16(a[i], bb[i], acc0); acc1 = mfma16(a[i + 1], bb[i + 1], acc1); } }
;     __syncthreads();
;     *(f32x4*)(red + wave * 256 + lane * 4) = acc0 + acc1;
;     __syncthreads();
;     if (wave == 0) { f32x4 s = {0.f, 0.f, 0.f, 0.f};
; #pragma unroll
;         for (int w = 0; w < 8; ++w) s += *(const f32x4*)(red + w * 256 + lane * 4);
	v_mfma_f32_16x16x32_bf16 v[36:39], v[184:187], v[200:203], v[36:39]
	v_mfma_f32_16x16x32_bf16 v[40:43], v[184:187], v[208:211], v[40:43]
	v_mfma_f32_16x16x32_bf16 v[44:47], v[184:187], v[216:219], v[44:47]
	v_mfma_f32_16x16x32_bf16 v[48:51], v[184:187], v[224:227], v[48:51]
	v_mfma_f32_16x16x32_bf16 v[52:55], v[192:195], v[200:203], v[52:55]
	v_mfma_f32_16x16x32_bf16 v[56:59], v[192:195], v[208:211], v[56:59]
	v_mfma_f32_16x16x32_bf16 v[60:63], v[192:195], v[216:219], v[60:63]
	v_mfma_f32_16x16x32_bf16 v[64:67], v[192:195], v[224:227], v[64:67]
	v_mfma_f32_16x16x32_bf16 v[36:39], v[188:191], v[204:207], v[36:39]
	v_mfma_f32_16x16x32_bf16 v[40:43], v[188:191], v[212:215], v[40:43]
	v_mfma_f32_16x16x32_bf16 v[44:47], v[188:191], v[220:223], v[44:47]
	v_mfma_f32_16x16x32_bf16 v[48:51], v[188:191], v[228:231], v[48:51]
	v_mfma_f32_16x16x32_bf16 v[52:55], v[196:199], v[204:207], v[52:55]
	v_mfma_f32_16x16x32_bf16 v[56:59], v[196:199], v[212:215], v[56:59]
	v_mfma_f32_16x16x32_bf16 v[60:63], v[196:199], v[220:223], v[60:63]
	v_mfma_f32_16x16x32_bf16 v[64:67], v[196:199], v[228:231], v[64:67]
	s_waitcnt vmcnt(0)
	ds_write_b128 v22, v[68:71]
	ds_write_b128 v118, v[72:75] offset:1024
	ds_write_b128 v22, v[76:79] offset:2048
	ds_write_b128 v118, v[80:83] offset:3072
	ds_write_b128 v22, v[84:87] offset:4096
	ds_write_b128 v118, v[88:91] offset:5120
	ds_write_b128 v22, v[92:95] offset:6144
	ds_write_b128 v118, v[96:99] offset:7168
	ds_write_b128 v22, v[100:103] offset:8192
	ds_write_b128 v118, v[104:107] offset:9216
	ds_write_b128 v22, v[108:111] offset:10240
	ds_write_b128 v118, v[112:115] offset:11264
	ds_read_b128 v[68:71], v18
	ds_read_b128 v[72:75], v19
	ds_read_b128 v[76:79], v18 offset:2048
	ds_read_b128 v[80:83], v19 offset:2048
	ds_read_b128 v[84:87], v18 offset:4096
	ds_read_b128 v[88:91], v19 offset:4096
	ds_read_b128 v[92:95], v18 offset:6144
	ds_read_b128 v[96:99], v19 offset:6144
	ds_read_b128 v[100:103], v18 offset:8192
	ds_read_b128 v[104:107], v19 offset:8192
	ds_read_b128 v[108:111], v18 offset:10240
	ds_read_b128 v[112:115], v19 offset:10240
	s_waitcnt lgkmcnt(0)
	v_mfma_f32_16x16x32_bf16 v[36:39], v[68:71], v[84:87], v[36:39]
	v_mfma_f32_16x16x32_bf16 v[40:43], v[68:71], v[92:95], v[40:43]
	v_mfma_f32_16x16x32_bf16 v[44:47], v[68:71], v[100:103], v[44:47]
	v_mfma_f32_16x16x32_bf16 v[48:51], v[68:71], v[108:111], v[48:51]
	v_mfma_f32_16x16x32_bf16 v[52:55], v[76:79], v[84:87], v[52:55]
	v_mfma_f32_16x16x32_bf16 v[56:59], v[76:79], v[92:95], v[56:59]
	v_mfma_f32_16x16x32_bf16 v[60:63], v[76:79], v[100:103], v[60:63]
	v_mfma_f32_16x16x32_bf16 v[64:67], v[76:79], v[108:111], v[64:67]
	v_mfma_f32_16x16x32_bf16 v[36:39], v[72:75], v[88:91], v[36:39]
	v_mfma_f32_16x16x32_bf16 v[40:43], v[72:75], v[96:99], v[40:43]
	v_mfma_f32_16x16x32_bf16 v[44:47], v[72:75], v[104:107], v[44:47]
	v_mfma_f32_16x16x32_bf16 v[48:51], v[72:75], v[112:115], v[48:51]
	v_mfma_f32_16x16x32_bf16 v[52:55], v[80:83], v[88:91], v[52:55]
	v_mfma_f32_16x16x32_bf16 v[56:59], v[80:83], v[96:99], v[56:59]
	v_mfma_f32_16x16x32_bf16 v[60:63], v[80:83], v[104:107], v[60:63]
	v_mfma_f32_16x16x32_bf16 v[64:67], v[80:83], v[112:115], v[64:67]
	s_barrier
	v_and_b32_e32 v18, 63, v172
	v_lshlrev_b32_e32 v18, 4, v18
	v_lshrrev_b32_e32 v19, 2, v116
	v_lshl_add_u32 v220, v116, 10, v18
	v_lshl_add_u32 v221, v19, 15, v220
	v_xor_b32_e32 v222, 1, v19
	v_lshl_add_u32 v222, v222, 15, v220
	s_nop 7
	ds_write_b128 v221, v[36:39] offset:0
	ds_write_b128 v222, v[52:55] offset:0
	ds_write_b128 v221, v[40:43] offset:8192
	ds_write_b128 v222, v[56:59] offset:8192
	ds_write_b128 v221, v[44:47] offset:16384
	ds_write_b128 v222, v[60:63] offset:16384
	ds_write_b128 v221, v[48:51] offset:24576
	ds_write_b128 v222, v[64:67] offset:24576
	s_waitcnt lgkmcnt(0)
	s_barrier
	v_lshl_add_u32 v19, v19, 2, v117
	v_lshl_add_u32 v19, v19, 13, v18
	ds_read_b128 v[68:71], v19 offset:0
	ds_read_b128 v[72:75], v19 offset:1024
	ds_read_b128 v[76:79], v19 offset:2048
	ds_read_b128 v[80:83], v19 offset:3072
	ds_read_b128 v[84:87], v19 offset:4096
	ds_read_b128 v[88:91], v19 offset:5120
	ds_read_b128 v[92:95], v19 offset:6144
	ds_read_b128 v[96:99], v19 offset:7168
	s_waitcnt lgkmcnt(0)
	v_add_f32_e32 v68, v68, v72
	v_add_f32_e32 v76, v76, v80
	v_add_f32_e32 v84, v84, v88
	v_add_f32_e32 v92, v92, v96
	v_add_f32_e32 v69, v69, v73
	v_add_f32_e32 v77, v77, v81
	v_add_f32_e32 v85, v85, v89
	v_add_f32_e32 v93, v93, v97
	v_add_f32_e32 v70, v70, v74
	v_add_f32_e32 v78, v78, v82
	v_add_f32_e32 v86, v86, v90
	v_add_f32_e32 v94, v94, v98
	v_add_f32_e32 v71, v71, v75
	v_add_f32_e32 v79, v79, v83
	v_add_f32_e32 v87, v87, v91
	v_add_f32_e32 v95, v95, v99
	v_add_f32_e32 v68, v68, v76
	v_add_f32_e32 v84, v84, v92
	v_add_f32_e32 v69, v69, v77
	v_add_f32_e32 v85, v85, v93
	v_add_f32_e32 v70, v70, v78
	v_add_f32_e32 v86, v86, v94
	v_add_f32_e32 v71, v71, v79
	v_add_f32_e32 v87, v87, v95
	v_add_f32_e32 v4, v68, v84
	v_add_f32_e32 v5, v69, v85
	v_add_f32_e32 v6, v70, v86
	v_add_f32_e32 v7, v71, v87
	v_mov_b32_e32 v8, 0
	v_mov_b32_e32 v9, 0
	v_mov_b32_e32 v10, 0
	v_mov_b32_e32 v11, 0
	v_mov_b32_e32 v8, v243
	v_mov_b32_e32 v32, v244
	v_mov_b32_e32 v216, v245
	v_mov_b32_e32 v217, v246
	v_mov_b32_e32 v218, v247
	v_lshl_add_u64 v[18:19], v[16:17], 2, s[14:15]
	s_mov_b32 s100, 0
	s_branch .Lsg1_join2
